# v33 + ffn_in k-loop issues the stage k+2 LDS-DMA mid-iteration after a second barrier (1.5-iteration load latency tolerance)
# speedup vs baseline: 1.0017x; 1.0017x over previous
; DEVI f32x4 mfma16(bf16x8 a, bf16x8 b, f32x4 c) { return __builtin_amdgcn_mfma_f32_16x16x32_bf16(a, b, c, 0, 0, 0); }
;     ...
;     auto issue = [&](int kt, int st) {
;         glds_tile8(va, vb, a0p + (size_t)kt * kstepA, Btile + (size_t)kt * 64, __builtin_amdgcn_readfirstlane(lds0 + st * 32768));
;     };
;     const int sw0 = (quad ^ (l16 >> 1)) * 16;
;     const int aoffb = (wr * 64 + l16) * 128, boffb = 16384 + (wc * 64 + l16) * 128;
;     if (!first_issued) issue(0, 0);
; #pragma unroll 1
;     for (int kt = 0; kt < nk; ++kt) {
;         asm volatile("s_waitcnt vmcnt(0)\n\ts_barrier" ::: "memory");
;         if (kt + 1 < nk) issue(kt + 1, (kt + 1) & 1);
;         const unsigned char* cs = sbase + (kt & 1) * 32768;
;         bf16x8 af0[4], bf0[4], af1[4], bf1[4];
; #pragma unroll
;         for (int i = 0; i < 4; ++i) { af0[i] = *(const bf16x8*)(cs + aoffb + i * 2048 + sw0); bf0[i] = *(const bf16x8*)(cs + boffb + i * 2048 + sw0); }
; #pragma unroll
;         for (int i = 0; i < 4; ++i) { af1[i] = *(const bf16x8*)(cs + aoffb + i * 2048 + (sw0 ^ 64)); bf1[i] = *(const bf16x8*)(cs + boffb + i * 2048 + (sw0 ^ 64)); }
;         __builtin_amdgcn_sched_barrier(0);
; #pragma unroll
;         for (int i = 0; i < 4; ++i)
; #pragma unroll
;             for (int j = 0; j < 4; ++j) acc[i][j] = SWAP ? mfma16(bf0[j], af0[i], acc[i][j]) : mfma16(af0[i], bf0[j], acc[i][j]);
;         __builtin_amdgcn_sched_barrier(0);
; #pragma unroll
;         for (int i = 0; i < 4; ++i)
; #pragma unroll
;             for (int j = 0; j < 4; ++j) acc[i][j] = SWAP ? mfma16(bf1[j], af1[i], acc[i][j]) : mfma16(af1[i], bf1[j], acc[i][j]);
.LBB0_788:
	s_and_b32 s24, s31, 0x8000
	v_add_u32_e32 v108, s24, v73
	v_or_b32_e32 v109, s24, v74
	v_add_u32_e32 v96, v108, v72
	v_add_u32_e32 v104, v109, v72
	v_add_u32_e32 v128, v108, v75
	ds_read_b128 v[76:79], v96
	ds_read_b128 v[80:83], v96 offset:2048
	ds_read_b128 v[84:87], v104 offset:16384
	ds_read_b128 v[88:91], v104 offset:18432
	ds_read_b128 v[92:95], v96 offset:4096
	ds_read_b128 v[96:99], v96 offset:6144
	ds_read_b128 v[100:103], v104 offset:20480
	ds_read_b128 v[104:107], v104 offset:22528
	v_add_u32_e32 v132, v109, v75
	ds_read_b128 v[108:111], v128
	ds_read_b128 v[112:115], v128 offset:2048
	ds_read_b128 v[116:119], v132 offset:16384
	ds_read_b128 v[120:123], v132 offset:18432
	ds_read_b128 v[124:127], v128 offset:4096
	ds_read_b128 v[128:131], v128 offset:6144
	ds_read_b128 v[138:141], v132 offset:20480
	ds_read_b128 v[158:161], v132 offset:22528
	s_waitcnt lgkmcnt(13)
	v_mfma_f32_16x16x32_bf16 v[58:61], v[84:87], v[76:79], v[58:61]
	s_waitcnt lgkmcnt(12)
	v_mfma_f32_16x16x32_bf16 v[62:65], v[88:91], v[76:79], v[62:65]
	s_waitcnt lgkmcnt(9)
	v_mfma_f32_16x16x32_bf16 v[50:53], v[100:103], v[76:79], v[50:53]
	s_waitcnt lgkmcnt(8)
	v_mfma_f32_16x16x32_bf16 v[54:57], v[104:107], v[76:79], v[54:57]
	v_mfma_f32_16x16x32_bf16 v[42:45], v[84:87], v[80:83], v[42:45]
	v_mfma_f32_16x16x32_bf16 v[46:49], v[88:91], v[80:83], v[46:49]
	v_mfma_f32_16x16x32_bf16 v[34:37], v[100:103], v[80:83], v[34:37]
	v_mfma_f32_16x16x32_bf16 v[38:41], v[104:107], v[80:83], v[38:41]
	v_mfma_f32_16x16x32_bf16 v[26:29], v[84:87], v[92:95], v[26:29]
	v_mfma_f32_16x16x32_bf16 v[30:33], v[88:91], v[92:95], v[30:33]
	v_mfma_f32_16x16x32_bf16 v[18:21], v[100:103], v[92:95], v[18:21]
	v_mfma_f32_16x16x32_bf16 v[22:25], v[104:107], v[92:95], v[22:25]
	v_mfma_f32_16x16x32_bf16 v[6:9], v[84:87], v[96:99], v[6:9]
	v_mfma_f32_16x16x32_bf16 v[14:17], v[88:91], v[96:99], v[14:17]
	v_mfma_f32_16x16x32_bf16 v[2:5], v[100:103], v[96:99], v[2:5]
	v_mfma_f32_16x16x32_bf16 v[10:13], v[104:107], v[96:99], v[10:13]
	s_add_u32 s10, s10, 0x80
	s_waitcnt lgkmcnt(5)
	v_mfma_f32_16x16x32_bf16 v[58:61], v[116:119], v[108:111], v[58:61]
	s_addc_u32 s11, s11, 0
	s_add_u32 s14, s14, 0x80
	s_addc_u32 s15, s15, 0
	s_waitcnt lgkmcnt(4)
	v_mfma_f32_16x16x32_bf16 v[62:65], v[120:123], v[108:111], v[62:65]
	s_mov_b32 s31, s34
	s_waitcnt lgkmcnt(1)
	v_mfma_f32_16x16x32_bf16 v[50:53], v[138:141], v[108:111], v[50:53]
	s_waitcnt lgkmcnt(0)
	v_mfma_f32_16x16x32_bf16 v[54:57], v[158:161], v[108:111], v[54:57]
	s_barrier
	s_cmp_lt_u32 s31, 0x78000
	s_cbranch_scc0 .Lffn_nomid
	s_add_i32 s24, s31, 0x8000
	s_and_b32 s24, s24, 0x8000
	s_add_i32 s24, s27, s24
	s_mov_b32 s25, m0
	s_mov_b32 m0, s24
	s_nop 0
	global_load_lds_dwordx4 v0, s[14:15]
	s_add_u32 m0, m0, 0x1000
	s_nop 0
	global_load_lds_dwordx4 v68, s[14:15]
	s_add_u32 m0, m0, 0x1000
	s_nop 0
	global_load_lds_dwordx4 v69, s[14:15]
	s_add_u32 m0, m0, 0x1000
	s_nop 0
	global_load_lds_dwordx4 v71, s[14:15]
	s_add_u32 m0, m0, 0x1000
	s_nop 0
	global_load_lds_dwordx4 v0, s[10:11]
	s_add_u32 m0, m0, 0x1000
	s_nop 0
	global_load_lds_dwordx4 v68, s[10:11]
	s_add_u32 m0, m0, 0x1000
	s_nop 0
	global_load_lds_dwordx4 v69, s[10:11]
	s_add_u32 m0, m0, 0x1000
	s_nop 0
	global_load_lds_dwordx4 v71, s[10:11]
	s_mov_b32 m0, s25
.Lffn_nomid:
	s_cmp_lg_u32 s34, 0x80000
	v_mfma_f32_16x16x32_bf16 v[42:45], v[116:119], v[112:115], v[42:45]
	v_mfma_f32_16x16x32_bf16 v[46:49], v[120:123], v[112:115], v[46:49]
	v_mfma_f32_16x16x32_bf16 v[34:37], v[138:141], v[112:115], v[34:37]
	v_mfma_f32_16x16x32_bf16 v[38:41], v[158:161], v[112:115], v[38:41]
	v_mfma_f32_16x16x32_bf16 v[26:29], v[116:119], v[124:127], v[26:29]
	v_mfma_f32_16x16x32_bf16 v[30:33], v[120:123], v[124:127], v[30:33]
	v_mfma_f32_16x16x32_bf16 v[18:21], v[138:141], v[124:127], v[18:21]
	v_mfma_f32_16x16x32_bf16 v[22:25], v[158:161], v[124:127], v[22:25]
	v_mfma_f32_16x16x32_bf16 v[6:9], v[116:119], v[128:131], v[6:9]
	v_mfma_f32_16x16x32_bf16 v[14:17], v[120:123], v[128:131], v[14:17]
	v_mfma_f32_16x16x32_bf16 v[2:5], v[138:141], v[128:131], v[2:5]
	v_mfma_f32_16x16x32_bf16 v[10:13], v[158:161], v[128:131], v[10:13]
	s_cbranch_scc0 .LBB0_793

;     ...
;     auto issue = [&](int kt, int st) {
;         glds_tile8(va, vb, a0p + (size_t)kt * kstepA, Btile + (size_t)kt * 64, __builtin_amdgcn_readfirstlane(lds0 + st * 32768));
;     };
;     const int sw0 = (quad ^ (l16 >> 1)) * 16;
;     const int aoffb = (wr * 64 + l16) * 128, boffb = 16384 + (wc * 64 + l16) * 128;
;     if (!first_issued) issue(0, 0);
; #pragma unroll 1
;     for (int kt = 0; kt < nk; ++kt) {
;         asm volatile("s_waitcnt vmcnt(0)\n\ts_barrier" ::: "memory");
;         if (kt + 1 < nk) issue(kt + 1, (kt + 1) & 1);
.Lffn_bar2:
	s_barrier
	s_and_b32 s24, s34, 0x8000
	s_add_i32 s24, s27, s24
	s_mov_b32 s25, m0
	s_mov_b32 m0, s24
	s_nop 0
	global_load_lds_dwordx4 v0, s[14:15]
	s_add_u32 m0, m0, 0x1000
	s_nop 0
	global_load_lds_dwordx4 v68, s[14:15]
	s_add_u32 m0, m0, 0x1000
	s_nop 0
	global_load_lds_dwordx4 v69, s[14:15]
	s_add_u32 m0, m0, 0x1000
	s_nop 0
	global_load_lds_dwordx4 v71, s[14:15]
	s_add_u32 m0, m0, 0x1000
	s_nop 0
	global_load_lds_dwordx4 v0, s[10:11]
	s_add_u32 m0, m0, 0x1000
	s_nop 0
	global_load_lds_dwordx4 v68, s[10:11]
	s_add_u32 m0, m0, 0x1000
	s_nop 0
	global_load_lds_dwordx4 v69, s[10:11]
	s_add_u32 m0, m0, 0x1000
	s_nop 0
	global_load_lds_dwordx4 v71, s[10:11]
	s_mov_b32 m0, s25
	s_branch .LBB0_788
.Lffn_k1:
	s_cmp_lg_u32 s31, 0x78000
	s_cbranch_scc0 .Lffn_last
	s_waitcnt vmcnt(8)
	s_barrier
	s_branch .LBB0_788
.Lffn_last:
	s_waitcnt vmcnt(0)
	s_barrier
	s_branch .LBB0_788
